# GU GEMM: peeled first K-iteration after each epilogue with wait counts that leave the epilogue stores in flight; As11 stage hoisted above the stores
# speedup vs baseline: 1.0007x; 1.0005x over previous
; template <class Epi, class Sched, bool ALIGN_EPI = false, bool SP2 = false>
; __device__ __forceinline__ void gemm_phase(PG8_LAS unsigned char* lds, const Gemm g, const Sched& S, const Epi& E) {
;     ...
;         const bool has_next = S.next(ui + 1, nxt);
;         const char* nA = has_next ? (const char*)g.A + (size_t)nxt.pm * tstep : cA; const char* nB = has_next ? (const char*)g.Bt + (size_t)nxt.pn * tstep : cB;
;         for (int t = 0; t < nt; t += 2) {
;             const bool last = (t == nt - 2);
;             const char* a1 = cA + (size_t)(t + 1) * kstep;
;             const char* a2 = last ? nA : cA + (size_t)(t + 2) * kstep; const char* b2 = last ? nB : cB + (size_t)(t + 2) * kstep;
;             const char* a3 = a2 + kstep; const char* b3 = b2 + kstep;
;     ...
; #pragma unroll
;         for (int a = 0; a < 2; ++a)
; #pragma unroll
;             for (int b = 0; b < 2; ++b)
; #pragma unroll
;                 for (int m = 0; m < 4; ++m)
; #pragma unroll
;                     for (int n = 0; n < 2; ++n) acc[a][b][m][n] = (f32x4){0.f, 0.f, 0.f, 0.f};
.LBB0_398:
	s_ashr_i32 s41, s40, 31
	s_lshl_b64 s[14:15], s[40:41], 19
	s_add_u32 s42, s0, s14
	s_addc_u32 s43, s1, s15
	s_and_b64 s[14:15], s[38:39], exec
	s_cselect_b32 s41, s43, s11
	s_cselect_b32 s46, s42, s10
	s_ashr_i32 s9, s8, 31
	s_lshl_b64 s[14:15], s[8:9], 19
	s_add_u32 s44, s19, s14
	s_addc_u32 s45, s20, s15
	s_and_b64 s[14:15], s[38:39], exec
	s_cselect_b32 s9, s45, s13
	s_cselect_b32 s47, s44, s12
	s_add_u32 s10, s10, 0x40080
	s_addc_u32 s11, s11, 0
	s_add_u32 s48, s12, 0x100
	v_mov_b32_e32 v0, 0
	s_addc_u32 s49, s13, 0
	s_mov_b32 s50, -2
	v_mov_b32_e32 v1, v0
	v_mov_b32_e32 v2, v0
	v_mov_b32_e32 v3, v0
	v_mov_b32_e32 v4, v0
	v_mov_b32_e32 v5, v0
	v_mov_b32_e32 v6, v0
	v_mov_b32_e32 v7, v0
	v_mov_b32_e32 v16, v0
	v_mov_b32_e32 v17, v0
	v_mov_b32_e32 v18, v0
	v_mov_b32_e32 v19, v0
	v_mov_b32_e32 v20, v0
	v_mov_b32_e32 v21, v0
	v_mov_b32_e32 v22, v0
	v_mov_b32_e32 v23, v0
	v_mov_b32_e32 v32, v0
	v_mov_b32_e32 v33, v0
	v_mov_b32_e32 v34, v0
	v_mov_b32_e32 v35, v0
	v_mov_b32_e32 v36, v0
	v_mov_b32_e32 v37, v0
	v_mov_b32_e32 v38, v0
	v_mov_b32_e32 v39, v0
	v_mov_b32_e32 v48, v0
	v_mov_b32_e32 v49, v0
	v_mov_b32_e32 v50, v0
	v_mov_b32_e32 v51, v0
	v_mov_b32_e32 v52, v0
	v_mov_b32_e32 v53, v0
	v_mov_b32_e32 v54, v0
	v_mov_b32_e32 v55, v0
	v_mov_b32_e32 v8, v0
	v_mov_b32_e32 v9, v0
	v_mov_b32_e32 v10, v0
	v_mov_b32_e32 v11, v0
	v_mov_b32_e32 v12, v0
	v_mov_b32_e32 v13, v0
	v_mov_b32_e32 v14, v0
	v_mov_b32_e32 v15, v0
	v_mov_b32_e32 v24, v0
	v_mov_b32_e32 v25, v0
	v_mov_b32_e32 v26, v0
	v_mov_b32_e32 v27, v0
	v_mov_b32_e32 v28, v0
	v_mov_b32_e32 v29, v0
	v_mov_b32_e32 v30, v0
	v_mov_b32_e32 v31, v0
	v_mov_b32_e32 v40, v0
	v_mov_b32_e32 v41, v0
	v_mov_b32_e32 v42, v0
	v_mov_b32_e32 v43, v0
	v_mov_b32_e32 v44, v0
	v_mov_b32_e32 v45, v0
	v_mov_b32_e32 v46, v0
	v_mov_b32_e32 v47, v0
	v_mov_b32_e32 v56, v0
	v_mov_b32_e32 v57, v0
	v_mov_b32_e32 v58, v0
	v_mov_b32_e32 v59, v0
	v_mov_b32_e32 v60, v0
	v_mov_b32_e32 v61, v0
	v_mov_b32_e32 v62, v0
	v_mov_b32_e32 v63, v0
	v_mov_b32_e32 v64, v0
	v_mov_b32_e32 v65, v0
	v_mov_b32_e32 v66, v0
	v_mov_b32_e32 v67, v0
	v_mov_b32_e32 v68, v0
	v_mov_b32_e32 v69, v0
	v_mov_b32_e32 v70, v0
	v_mov_b32_e32 v71, v0
	v_mov_b32_e32 v80, v0
	v_mov_b32_e32 v81, v0
	v_mov_b32_e32 v82, v0
	v_mov_b32_e32 v83, v0
	v_mov_b32_e32 v84, v0
	v_mov_b32_e32 v85, v0
	v_mov_b32_e32 v86, v0
	v_mov_b32_e32 v87, v0
	v_mov_b32_e32 v96, v0
	v_mov_b32_e32 v97, v0
	v_mov_b32_e32 v98, v0
	v_mov_b32_e32 v99, v0
	v_mov_b32_e32 v100, v0
	v_mov_b32_e32 v101, v0
	v_mov_b32_e32 v102, v0
	v_mov_b32_e32 v103, v0
	v_mov_b32_e32 v112, v0
	v_mov_b32_e32 v113, v0
	v_mov_b32_e32 v114, v0
	v_mov_b32_e32 v115, v0
	v_mov_b32_e32 v116, v0
	v_mov_b32_e32 v117, v0
	v_mov_b32_e32 v118, v0
	v_mov_b32_e32 v119, v0
	v_mov_b32_e32 v72, v0
	v_mov_b32_e32 v73, v0
	v_mov_b32_e32 v74, v0
	v_mov_b32_e32 v75, v0
	v_mov_b32_e32 v76, v0
	v_mov_b32_e32 v77, v0
	v_mov_b32_e32 v78, v0
	v_mov_b32_e32 v79, v0
	v_mov_b32_e32 v88, v0
	v_mov_b32_e32 v89, v0
	v_mov_b32_e32 v90, v0
	v_mov_b32_e32 v91, v0
	v_mov_b32_e32 v92, v0
	v_mov_b32_e32 v93, v0
	v_mov_b32_e32 v94, v0
	v_mov_b32_e32 v95, v0
	v_mov_b32_e32 v104, v0
	v_mov_b32_e32 v105, v0
	v_mov_b32_e32 v106, v0
	v_mov_b32_e32 v107, v0
	v_mov_b32_e32 v108, v0
	v_mov_b32_e32 v109, v0
	v_mov_b32_e32 v110, v0
	v_mov_b32_e32 v111, v0
	v_mov_b32_e32 v120, v0
	v_mov_b32_e32 v121, v0
	v_mov_b32_e32 v122, v0
	v_mov_b32_e32 v123, v0
	v_mov_b32_e32 v124, v0
	v_mov_b32_e32 v125, v0
	v_mov_b32_e32 v126, v0
	v_mov_b32_e32 v127, v0
	s_cmp_lg_u32 s31, 1
	s_cbranch_scc1 .Lpeel_act

; #define PG8_LAS __attribute__((address_space(3)))
; __device__ __forceinline__ unsigned cvt_pk_bf16(float lo, float hi) { unsigned r; asm volatile("v_cvt_pk_bf16_f32 %0, %1, %2" : "=v"(r) : "v"(lo), "v"(hi)); return r; }
; __device__ __forceinline__ float silu_mul(float g, float u) { return g * u * __builtin_amdgcn_rcpf(1.0f + __builtin_amdgcn_exp2f(-1.4426950408889634f * g)); }
; #define PG8_SCHED __builtin_amdgcn_sched_barrier(0)
;     __device__ __forceinline__ void operator()(const f32x4 (&acc)[2][2][4][2], const Unit& u, int wr, int wc, int fr, int fq) const {
;         const int row0 = u.pm * BM + wr * 64 + fr, col0 = u.pn * HALF + wc * 32 + 8 * fq;
;         float rsv[8]; { const PG8_LAS float* t_ = rt.rows(u.pm) + wr * 64 + fr;
; #pragma unroll
;             for (int it = 0; it < 8; ++it) rsv[it] = t_[(it >> 2) * HALF + (it & 3) * 16]; }
; #pragma unroll
;         for (int ai = 0; ai < 2; ++ai)
; #pragma unroll
;             for (int m = 0; m < 4; ++m) {
;                 const int row = row0 + ai * HALF + m * 16; const float rs = rsv[ai * 4 + m];
;                 const f32x4 g0 = acc[ai][0][m][0] * rs, g1 = acc[ai][0][m][1] * rs, u0 = acc[ai][1][m][0] * rs, u1 = acc[ai][1][m][1] * rs;
;                 u32x4e w;
;                 w.x = cvt_pk_bf16(silu_mul(g0[0], u0[0]), silu_mul(g0[1], u0[1])); w.y = cvt_pk_bf16(silu_mul(g0[2], u0[2]), silu_mul(g0[3], u0[3]));
;                 w.z = cvt_pk_bf16(silu_mul(g1[0], u1[0]), silu_mul(g1[1], u1[1])); w.w = cvt_pk_bf16(silu_mul(g1[2], u1[2]), silu_mul(g1[3], u1[3]));
;                 *(u32x4e*)(O + (size_t)row * ldo + col0) = w;
;             }
; template <class Epi, class Sched, bool ALIGN_EPI = false, bool SP2 = false>
; __device__ __forceinline__ void gemm_phase(PG8_LAS unsigned char* lds, const Gemm g, const Sched& S, const Epi& E) {
;     ...
;             const char* a2 = last ? nA : cA + (size_t)(t + 2) * kstep; const char* b2 = last ? nB : cB + (size_t)(t + 2) * kstep;
;             const char* a3 = a2 + kstep; const char* b3 = b2 + kstep;
;             if (last && has_next) S.a_ready(nxt);
;             if constexpr (SP2) {
;             PG8_LDB(B0, 0, 0); PG8_LDB(B1, 0, 1); PG8_SCHED; PG8_LDA(At, 0, 0); PG8_STAGE(PG8_SA(1, 1), a1 + hstep, voffA);
.LBB0_402:
	s_add_u32 s100, s46, 0x40080
	s_addc_u32 s101, s41, 0
	v_lshl_add_u64 v[224:225], s[100:101], 0, v[134:135]
	s_add_i32 m0, s25, 0xc000
	v_lshl_add_u64 v[226:227], s[100:101], 0, v[136:137]
	global_load_lds_dwordx4 v[224:225], off
	s_add_i32 m0, s25, 0xe000
	s_nop 0
	global_load_lds_dwordx4 v[226:227], off
	s_cmp_eq_u32 s35, s16
	s_cselect_b32 s9, 0x200, s23
	s_cmp_lg_u32 s35, s17
	s_cselect_b32 s9, s9, 0x100
	s_cmp_lg_u32 s35, s18
	s_cselect_b32 s9, s9, 0
	v_lshl_add_u32 v138, s9, 2, v150
	ds_read2_b32 v[144:145], v138 offset1:16
	ds_read2_b32 v[142:143], v138 offset0:32 offset1:48
	ds_read2_b32 v[140:141], v138 offset0:128 offset1:144
	ds_read2_b32 v[138:139], v138 offset0:160 offset1:176
	v_lshl_or_b32 v146, s34, 7, v151
	s_waitcnt lgkmcnt(0)
	v_pk_mul_f32 v[124:125], v[124:125], v[144:145] op_sel_hi:[1,0]
	v_pk_mul_f32 v[116:117], v[116:117], v[144:145] op_sel_hi:[1,0]
	v_pk_mul_f32 v[126:127], v[126:127], v[144:145] op_sel_hi:[1,0]
	v_mul_f32_e32 v116, v124, v116
	v_mul_f32_e32 v124, 0xbfb8aa3b, v124
	v_exp_f32_e32 v124, v124
	v_mul_f32_e32 v117, v125, v117
	v_pk_mul_f32 v[118:119], v[118:119], v[144:145] op_sel_hi:[1,0]
	v_pk_mul_f32 v[120:121], v[120:121], v[144:145] op_sel_hi:[1,0]
	v_add_f32_e32 v124, 1.0, v124
	v_rcp_f32_e32 v124, v124
	v_pk_mul_f32 v[112:113], v[112:113], v[144:145] op_sel_hi:[1,0]
	v_pk_mul_f32 v[122:123], v[122:123], v[144:145] op_sel_hi:[1,0]
	v_mul_f32_e32 v112, v120, v112
	v_mul_f32_e32 v116, v116, v124
	v_mul_f32_e32 v124, 0xbfb8aa3b, v125
	v_exp_f32_e32 v124, v124
	v_mul_f32_e32 v113, v121, v113
	v_pk_mul_f32 v[114:115], v[114:115], v[144:145] op_sel_hi:[1,0]
	v_lshl_add_u32 v153, s35, 8, v148
	v_add_f32_e32 v124, 1.0, v124
	v_rcp_f32_e32 v124, v124
	v_ashrrev_i32_e32 v147, 31, v146
	v_pk_mul_f32 v[92:93], v[92:93], v[142:143] op_sel_hi:[1,0]
	v_pk_mul_f32 v[84:85], v[84:85], v[142:143] op_sel_hi:[1,0]
	v_mul_f32_e32 v117, v117, v124
	v_cvt_pk_bf16_f32 v116, v116, v117
	v_mul_f32_e32 v117, v126, v118
	v_mul_f32_e32 v118, 0xbfb8aa3b, v126
	v_exp_f32_e32 v118, v118
	v_pk_mul_f32 v[94:95], v[94:95], v[142:143] op_sel_hi:[1,0]
	v_pk_mul_f32 v[86:87], v[86:87], v[142:143] op_sel_hi:[1,0]
	v_pk_mul_f32 v[88:89], v[88:89], v[142:143] op_sel_hi:[1,0]
	v_add_f32_e32 v118, 1.0, v118
	v_rcp_f32_e32 v118, v118
	v_pk_mul_f32 v[90:91], v[90:91], v[142:143] op_sel_hi:[1,0]
	v_pk_mul_f32 v[60:61], v[60:61], v[140:141] op_sel_hi:[1,0]
	v_pk_mul_f32 v[52:53], v[52:53], v[140:141] op_sel_hi:[1,0]
	v_mul_f32_e32 v117, v117, v118
	v_mul_f32_e32 v118, v127, v119
	v_mul_f32_e32 v119, 0xbfb8aa3b, v127
	v_exp_f32_e32 v119, v119
	v_pk_mul_f32 v[62:63], v[62:63], v[140:141] op_sel_hi:[1,0]
	v_pk_mul_f32 v[54:55], v[54:55], v[140:141] op_sel_hi:[1,0]
	v_pk_mul_f32 v[56:57], v[56:57], v[140:141] op_sel_hi:[1,0]
	v_add_f32_e32 v119, 1.0, v119
	v_rcp_f32_e32 v119, v119
	v_pk_mul_f32 v[58:59], v[58:59], v[140:141] op_sel_hi:[1,0]
	v_pk_mul_f32 v[28:29], v[28:29], v[138:139] op_sel_hi:[1,0]
	v_pk_mul_f32 v[20:21], v[20:21], v[138:139] op_sel_hi:[1,0]
	v_mul_f32_e32 v118, v118, v119
	v_cvt_pk_bf16_f32 v117, v117, v118
	v_mul_f32_e32 v118, 0xbfb8aa3b, v120
	v_exp_f32_e32 v118, v118
	v_pk_mul_f32 v[30:31], v[30:31], v[138:139] op_sel_hi:[1,0]
	v_pk_mul_f32 v[22:23], v[22:23], v[138:139] op_sel_hi:[1,0]
	v_pk_mul_f32 v[24:25], v[24:25], v[138:139] op_sel_hi:[1,0]
	v_add_f32_e32 v118, 1.0, v118
	v_rcp_f32_e32 v118, v118
	v_pk_mul_f32 v[26:27], v[26:27], v[138:139] op_sel_hi:[1,0]
	s_andn2_b64 vcc, exec, s[38:39]
	v_mul_f32_e32 v112, v112, v118
	v_mul_f32_e32 v118, 0xbfb8aa3b, v121
	v_exp_f32_e32 v118, v118
	s_nop 0
	v_add_f32_e32 v118, 1.0, v118
	v_rcp_f32_e32 v118, v118
	s_nop 0
	v_mul_f32_e32 v113, v113, v118
	v_cvt_pk_bf16_f32 v118, v112, v113
	v_mul_f32_e32 v113, 0xbfb8aa3b, v122
	v_mul_f32_e32 v112, v122, v114
	v_exp_f32_e32 v113, v113
	v_mul_f32_e32 v114, 0xbfb8aa3b, v123
	v_exp_f32_e32 v114, v114
	v_add_f32_e32 v113, 1.0, v113
	v_rcp_f32_e32 v113, v113
	v_add_f32_e32 v114, 1.0, v114
	v_rcp_f32_e32 v114, v114
	v_mul_f32_e32 v112, v112, v113
	v_mul_f32_e32 v113, v123, v115
	v_mul_f32_e32 v113, v113, v114
	v_cvt_pk_bf16_f32 v119, v112, v113
	v_mov_b64_e32 v[112:113], s[90:91]
	v_mad_i64_i32 v[120:121], s[10:11], v153, s24, v[112:113]
	v_lshlrev_b64 v[114:115], 1, v[146:147]
	v_lshl_add_u64 v[120:121], v[120:121], 0, v[114:115]
	global_store_dwordx4 v[120:121], v[116:119], off
	s_nop 1
	v_or_b32_e32 v117, 16, v153
	v_mov_b32_e32 v116, v145
	v_pk_mul_f32 v[108:109], v[108:109], v[116:117] op_sel_hi:[1,0]
	v_pk_mul_f32 v[100:101], v[100:101], v[116:117] op_sel_hi:[1,0]
	v_pk_mul_f32 v[118:119], v[98:99], v[116:117] op_sel_hi:[1,0]
	v_pk_mul_f32 v[98:99], v[96:97], v[116:117] op_sel_hi:[1,0]
	v_mul_f32_e32 v97, 0xbfb8aa3b, v108
	v_mul_f32_e32 v96, v108, v100
	v_exp_f32_e32 v97, v97
	v_mul_f32_e32 v100, 0xbfb8aa3b, v109
	v_exp_f32_e32 v100, v100
	v_pk_mul_f32 v[110:111], v[110:111], v[116:117] op_sel_hi:[1,0]
	v_add_f32_e32 v97, 1.0, v97
	v_rcp_f32_e32 v97, v97
	v_add_f32_e32 v100, 1.0, v100
	v_rcp_f32_e32 v100, v100
	v_pk_mul_f32 v[102:103], v[102:103], v[116:117] op_sel_hi:[1,0]
	v_mul_f32_e32 v96, v96, v97
	v_mul_f32_e32 v97, v109, v101
	v_mul_f32_e32 v97, v97, v100
	v_mul_f32_e32 v100, 0xbfb8aa3b, v110
	v_exp_f32_e32 v100, v100
	v_mul_f32_e32 v101, 0xbfb8aa3b, v111
	v_exp_f32_e32 v101, v101
	v_cvt_pk_bf16_f32 v96, v96, v97
	v_add_f32_e32 v100, 1.0, v100
	v_rcp_f32_e32 v100, v100
	v_add_f32_e32 v101, 1.0, v101
	v_rcp_f32_e32 v101, v101
	v_mul_f32_e32 v97, v110, v102
	v_mul_f32_e32 v97, v97, v100
	v_mul_f32_e32 v100, v111, v103
	v_pk_mul_f32 v[104:105], v[104:105], v[116:117] op_sel_hi:[1,0]
	v_mul_f32_e32 v100, v100, v101
; __device__ __forceinline__ unsigned cvt_pk_bf16(float lo, float hi) { unsigned r; asm volatile("v_cvt_pk_bf16_f32 %0, %1, %2" : "=v"(r) : "v"(lo), "v"(hi)); return r; }
; __device__ __forceinline__ float silu_mul(float g, float u) { return g * u * __builtin_amdgcn_rcpf(1.0f + __builtin_amdgcn_exp2f(-1.4426950408889634f * g)); }
;     __device__ __forceinline__ void operator()(const f32x4 (&acc)[2][2][4][2], const Unit& u, int wr, int wc, int fr, int fq) const {
;     ...
;             for (int m = 0; m < 4; ++m) {
;                 const int row = row0 + ai * HALF + m * 16; const float rs = rsv[ai * 4 + m];
;                 const f32x4 g0 = acc[ai][0][m][0] * rs, g1 = acc[ai][0][m][1] * rs, u0 = acc[ai][1][m][0] * rs, u1 = acc[ai][1][m][1] * rs;
;                 u32x4e w;
;                 w.x = cvt_pk_bf16(silu_mul(g0[0], u0[0]), silu_mul(g0[1], u0[1])); w.y = cvt_pk_bf16(silu_mul(g0[2], u0[2]), silu_mul(g0[3], u0[3]));
;                 w.z = cvt_pk_bf16(silu_mul(g1[0], u1[0]), silu_mul(g1[1], u1[1])); w.w = cvt_pk_bf16(silu_mul(g1[2], u1[2]), silu_mul(g1[3], u1[3]));
;                 *(u32x4e*)(O + (size_t)row * ldo + col0) = w;
	v_cvt_pk_bf16_f32 v97, v97, v100
	v_mul_f32_e32 v100, 0xbfb8aa3b, v104
	v_exp_f32_e32 v100, v100
	v_mul_f32_e32 v98, v104, v98
	v_pk_mul_f32 v[106:107], v[106:107], v[116:117] op_sel_hi:[1,0]
	v_mul_f32_e32 v99, v105, v99
	v_add_f32_e32 v100, 1.0, v100
	v_rcp_f32_e32 v100, v100
	v_mul_f32_e32 v101, 0xbfb8aa3b, v107
	v_exp_f32_e32 v101, v101
	v_mul_f32_e32 v98, v98, v100
	v_mul_f32_e32 v100, 0xbfb8aa3b, v105
	v_exp_f32_e32 v100, v100
	v_add_f32_e32 v101, 1.0, v101
	v_rcp_f32_e32 v101, v101
	v_add_f32_e32 v100, 1.0, v100
	v_rcp_f32_e32 v100, v100
	s_nop 0
	v_mul_f32_e32 v99, v99, v100
	v_mul_f32_e32 v100, 0xbfb8aa3b, v106
	v_exp_f32_e32 v100, v100
	v_cvt_pk_bf16_f32 v98, v98, v99
	v_mul_f32_e32 v99, v106, v118
	v_add_f32_e32 v100, 1.0, v100
	v_rcp_f32_e32 v100, v100
	s_nop 0
	v_mul_f32_e32 v99, v99, v100
	v_mul_f32_e32 v100, v107, v119
	v_mul_f32_e32 v100, v100, v101
	v_cvt_pk_bf16_f32 v99, v99, v100
	v_mad_i64_i32 v[100:101], s[10:11], v117, s24, v[112:113]
	v_lshl_add_u64 v[100:101], v[100:101], 0, v[114:115]
	global_store_dwordx4 v[100:101], v[96:99], off
	s_nop 1
	v_pk_mul_f32 v[96:97], v[82:83], v[142:143] op_sel_hi:[1,0]
	v_pk_mul_f32 v[82:83], v[80:81], v[142:143] op_sel_hi:[1,0]
	v_mul_f32_e32 v81, 0xbfb8aa3b, v92
	v_mul_f32_e32 v80, v92, v84
	v_exp_f32_e32 v81, v81
	v_mul_f32_e32 v84, 0xbfb8aa3b, v93
	v_exp_f32_e32 v84, v84
	v_mul_f32_e32 v82, v88, v82
	v_add_f32_e32 v81, 1.0, v81
	v_rcp_f32_e32 v81, v81
	v_add_f32_e32 v84, 1.0, v84
	v_rcp_f32_e32 v84, v84
	v_mul_f32_e32 v83, v89, v83
	v_mul_f32_e32 v80, v80, v81
	v_mul_f32_e32 v81, v93, v85
	v_mul_f32_e32 v81, v81, v84
	v_mul_f32_e32 v84, 0xbfb8aa3b, v94
	v_exp_f32_e32 v84, v84
	v_mul_f32_e32 v85, 0xbfb8aa3b, v95
	v_exp_f32_e32 v85, v85
	v_cvt_pk_bf16_f32 v80, v80, v81
	v_add_f32_e32 v84, 1.0, v84
	v_rcp_f32_e32 v84, v84
	v_add_f32_e32 v85, 1.0, v85
	v_rcp_f32_e32 v85, v85
	v_mul_f32_e32 v81, v94, v86
	v_mul_f32_e32 v81, v81, v84
	v_mul_f32_e32 v84, v95, v87
	v_mul_f32_e32 v84, v84, v85
	v_cvt_pk_bf16_f32 v81, v81, v84
	v_mul_f32_e32 v84, 0xbfb8aa3b, v88
	v_exp_f32_e32 v84, v84
	v_mul_f32_e32 v85, 0xbfb8aa3b, v91
	v_exp_f32_e32 v85, v85
	v_or_b32_e32 v98, 32, v153
	v_add_f32_e32 v84, 1.0, v84
	v_rcp_f32_e32 v84, v84
	v_add_f32_e32 v85, 1.0, v85
	v_rcp_f32_e32 v85, v85
	v_mul_f32_e32 v82, v82, v84
	v_mul_f32_e32 v84, 0xbfb8aa3b, v89
	v_exp_f32_e32 v84, v84
	s_nop 0
	v_add_f32_e32 v84, 1.0, v84
	v_rcp_f32_e32 v84, v84
	s_nop 0
	v_mul_f32_e32 v83, v83, v84
	v_mul_f32_e32 v84, 0xbfb8aa3b, v90
	v_exp_f32_e32 v84, v84
	v_cvt_pk_bf16_f32 v82, v82, v83
	v_mul_f32_e32 v83, v90, v96
	v_add_f32_e32 v84, 1.0, v84
	v_rcp_f32_e32 v84, v84
	s_nop 0
	v_mul_f32_e32 v83, v83, v84
	v_mul_f32_e32 v84, v91, v97
	v_mul_f32_e32 v84, v84, v85
	v_cvt_pk_bf16_f32 v83, v83, v84
	v_mad_i64_i32 v[84:85], s[10:11], v98, s24, v[112:113]
	v_lshl_add_u64 v[84:85], v[84:85], 0, v[114:115]
	global_store_dwordx4 v[84:85], v[80:83], off
	s_nop 1
	v_or_b32_e32 v81, 48, v153
	v_mov_b32_e32 v80, v143
	v_pk_mul_f32 v[76:77], v[76:77], v[80:81] op_sel_hi:[1,0]
	v_pk_mul_f32 v[68:69], v[68:69], v[80:81] op_sel_hi:[1,0]
	v_pk_mul_f32 v[82:83], v[66:67], v[80:81] op_sel_hi:[1,0]
	v_pk_mul_f32 v[66:67], v[64:65], v[80:81] op_sel_hi:[1,0]
	v_mul_f32_e32 v65, 0xbfb8aa3b, v76
	v_mul_f32_e32 v64, v76, v68
	v_exp_f32_e32 v65, v65
	v_mul_f32_e32 v68, 0xbfb8aa3b, v77
	v_exp_f32_e32 v68, v68
	v_pk_mul_f32 v[78:79], v[78:79], v[80:81] op_sel_hi:[1,0]
	v_add_f32_e32 v65, 1.0, v65
	v_rcp_f32_e32 v65, v65
	v_add_f32_e32 v68, 1.0, v68
	v_rcp_f32_e32 v68, v68
	v_pk_mul_f32 v[70:71], v[70:71], v[80:81] op_sel_hi:[1,0]
	v_mul_f32_e32 v64, v64, v65
	v_mul_f32_e32 v65, v77, v69
	v_mul_f32_e32 v65, v65, v68
	v_mul_f32_e32 v68, 0xbfb8aa3b, v78
	v_exp_f32_e32 v68, v68
	v_mul_f32_e32 v69, 0xbfb8aa3b, v79
	v_exp_f32_e32 v69, v69
	v_cvt_pk_bf16_f32 v64, v64, v65
	v_add_f32_e32 v68, 1.0, v68
	v_rcp_f32_e32 v68, v68
	v_add_f32_e32 v69, 1.0, v69
	v_rcp_f32_e32 v69, v69
	v_mul_f32_e32 v65, v78, v70
	v_mul_f32_e32 v65, v65, v68
	v_mul_f32_e32 v68, v79, v71
	v_pk_mul_f32 v[72:73], v[72:73], v[80:81] op_sel_hi:[1,0]
	v_mul_f32_e32 v68, v68, v69
	v_cvt_pk_bf16_f32 v65, v65, v68
	v_mul_f32_e32 v68, 0xbfb8aa3b, v72
	v_exp_f32_e32 v68, v68
	v_mul_f32_e32 v66, v72, v66
	v_pk_mul_f32 v[74:75], v[74:75], v[80:81] op_sel_hi:[1,0]
	v_mul_f32_e32 v67, v73, v67
	v_add_f32_e32 v68, 1.0, v68
	v_rcp_f32_e32 v68, v68
	v_mul_f32_e32 v69, 0xbfb8aa3b, v75
	v_exp_f32_e32 v69, v69
	v_mul_f32_e32 v66, v66, v68
	v_mul_f32_e32 v68, 0xbfb8aa3b, v73
	v_exp_f32_e32 v68, v68
	v_add_f32_e32 v69, 1.0, v69
	v_rcp_f32_e32 v69, v69
	v_add_f32_e32 v68, 1.0, v68
	v_rcp_f32_e32 v68, v68
	s_nop 0
	v_mul_f32_e32 v67, v67, v68
	v_mul_f32_e32 v68, 0xbfb8aa3b, v74
	v_exp_f32_e32 v68, v68
	v_cvt_pk_bf16_f32 v66, v66, v67
	v_mul_f32_e32 v67, v74, v82
	v_add_f32_e32 v68, 1.0, v68
	v_rcp_f32_e32 v68, v68
	s_nop 0
	v_mul_f32_e32 v67, v67, v68
	v_mul_f32_e32 v68, v75, v83
	v_mul_f32_e32 v68, v68, v69
	v_cvt_pk_bf16_f32 v67, v67, v68
	v_mad_i64_i32 v[68:69], s[10:11], v81, s24, v[112:113]
	v_lshl_add_u64 v[68:69], v[68:69], 0, v[114:115]
	global_store_dwordx4 v[68:69], v[64:67], off
	s_nop 1
	v_pk_mul_f32 v[64:65], v[50:51], v[140:141] op_sel_hi:[1,0]
	v_pk_mul_f32 v[50:51], v[48:49], v[140:141] op_sel_hi:[1,0]
	v_mul_f32_e32 v49, 0xbfb8aa3b, v60
	v_mul_f32_e32 v48, v60, v52
	v_exp_f32_e32 v49, v49
	v_mul_f32_e32 v52, 0xbfb8aa3b, v61
	v_exp_f32_e32 v52, v52
	v_mul_f32_e32 v50, v56, v50
	v_add_f32_e32 v49, 1.0, v49
	v_rcp_f32_e32 v49, v49
	v_add_f32_e32 v52, 1.0, v52
	v_rcp_f32_e32 v52, v52
	v_mul_f32_e32 v51, v57, v51
	v_mul_f32_e32 v48, v48, v49
	v_mul_f32_e32 v49, v61, v53
	v_mul_f32_e32 v49, v49, v52
; __device__ __forceinline__ unsigned cvt_pk_bf16(float lo, float hi) { unsigned r; asm volatile("v_cvt_pk_bf16_f32 %0, %1, %2" : "=v"(r) : "v"(lo), "v"(hi)); return r; }
; __device__ __forceinline__ float silu_mul(float g, float u) { return g * u * __builtin_amdgcn_rcpf(1.0f + __builtin_amdgcn_exp2f(-1.4426950408889634f * g)); }
;     __device__ __forceinline__ void operator()(const f32x4 (&acc)[2][2][4][2], const Unit& u, int wr, int wc, int fr, int fq) const {
;     ...
;             for (int m = 0; m < 4; ++m) {
;                 const int row = row0 + ai * HALF + m * 16; const float rs = rsv[ai * 4 + m];
;                 const f32x4 g0 = acc[ai][0][m][0] * rs, g1 = acc[ai][0][m][1] * rs, u0 = acc[ai][1][m][0] * rs, u1 = acc[ai][1][m][1] * rs;
;                 u32x4e w;
;                 w.x = cvt_pk_bf16(silu_mul(g0[0], u0[0]), silu_mul(g0[1], u0[1])); w.y = cvt_pk_bf16(silu_mul(g0[2], u0[2]), silu_mul(g0[3], u0[3]));
;                 w.z = cvt_pk_bf16(silu_mul(g1[0], u1[0]), silu_mul(g1[1], u1[1])); w.w = cvt_pk_bf16(silu_mul(g1[2], u1[2]), silu_mul(g1[3], u1[3]));
;                 *(u32x4e*)(O + (size_t)row * ldo + col0) = w;
	v_mul_f32_e32 v52, 0xbfb8aa3b, v62
	v_exp_f32_e32 v52, v52
	v_mul_f32_e32 v53, 0xbfb8aa3b, v63
	v_exp_f32_e32 v53, v53
	v_cvt_pk_bf16_f32 v48, v48, v49
	v_add_f32_e32 v52, 1.0, v52
	v_rcp_f32_e32 v52, v52
	v_add_f32_e32 v53, 1.0, v53
	v_rcp_f32_e32 v53, v53
	v_mul_f32_e32 v49, v62, v54
	v_mul_f32_e32 v49, v49, v52
	v_mul_f32_e32 v52, v63, v55
	v_mul_f32_e32 v52, v52, v53
	v_cvt_pk_bf16_f32 v49, v49, v52
	v_mul_f32_e32 v52, 0xbfb8aa3b, v56
	v_exp_f32_e32 v52, v52
	v_mul_f32_e32 v53, 0xbfb8aa3b, v59
	v_exp_f32_e32 v53, v53
	v_add_u32_e32 v66, 0x80, v153
	v_add_f32_e32 v52, 1.0, v52
	v_rcp_f32_e32 v52, v52
	v_add_f32_e32 v53, 1.0, v53
	v_rcp_f32_e32 v53, v53
	v_mul_f32_e32 v50, v50, v52
	v_mul_f32_e32 v52, 0xbfb8aa3b, v57
	v_exp_f32_e32 v52, v52
	s_nop 0
	v_add_f32_e32 v52, 1.0, v52
	v_rcp_f32_e32 v52, v52
	s_nop 0
	v_mul_f32_e32 v51, v51, v52
	v_mul_f32_e32 v52, 0xbfb8aa3b, v58
	v_exp_f32_e32 v52, v52
	v_cvt_pk_bf16_f32 v50, v50, v51
	v_mul_f32_e32 v51, v58, v64
	v_add_f32_e32 v52, 1.0, v52
	v_rcp_f32_e32 v52, v52
	s_nop 0
	v_mul_f32_e32 v51, v51, v52
	v_mul_f32_e32 v52, v59, v65
	v_mul_f32_e32 v52, v52, v53
	v_cvt_pk_bf16_f32 v51, v51, v52
	v_mad_i64_i32 v[52:53], s[10:11], v66, s24, v[112:113]
	v_lshl_add_u64 v[52:53], v[52:53], 0, v[114:115]
	global_store_dwordx4 v[52:53], v[48:51], off
	s_nop 1
	v_add_u32_e32 v49, 0x90, v153
	v_mov_b32_e32 v48, v141
	v_pk_mul_f32 v[44:45], v[44:45], v[48:49] op_sel_hi:[1,0]
	v_pk_mul_f32 v[36:37], v[36:37], v[48:49] op_sel_hi:[1,0]
	v_pk_mul_f32 v[50:51], v[34:35], v[48:49] op_sel_hi:[1,0]
	v_pk_mul_f32 v[34:35], v[32:33], v[48:49] op_sel_hi:[1,0]
	v_mul_f32_e32 v33, 0xbfb8aa3b, v44
	v_mul_f32_e32 v32, v44, v36
	v_exp_f32_e32 v33, v33
	v_mul_f32_e32 v36, 0xbfb8aa3b, v45
	v_exp_f32_e32 v36, v36
	v_pk_mul_f32 v[46:47], v[46:47], v[48:49] op_sel_hi:[1,0]
	v_add_f32_e32 v33, 1.0, v33
	v_rcp_f32_e32 v33, v33
	v_add_f32_e32 v36, 1.0, v36
	v_rcp_f32_e32 v36, v36
	v_pk_mul_f32 v[38:39], v[38:39], v[48:49] op_sel_hi:[1,0]
	v_mul_f32_e32 v32, v32, v33
	v_mul_f32_e32 v33, v45, v37
	v_mul_f32_e32 v33, v33, v36
	v_mul_f32_e32 v36, 0xbfb8aa3b, v46
	v_exp_f32_e32 v36, v36
	v_mul_f32_e32 v37, 0xbfb8aa3b, v47
	v_exp_f32_e32 v37, v37
	v_cvt_pk_bf16_f32 v32, v32, v33
	v_add_f32_e32 v36, 1.0, v36
	v_rcp_f32_e32 v36, v36
	v_add_f32_e32 v37, 1.0, v37
	v_rcp_f32_e32 v37, v37
	v_mul_f32_e32 v33, v46, v38
	v_mul_f32_e32 v33, v33, v36
	v_mul_f32_e32 v36, v47, v39
	v_pk_mul_f32 v[40:41], v[40:41], v[48:49] op_sel_hi:[1,0]
	v_mul_f32_e32 v36, v36, v37
	v_cvt_pk_bf16_f32 v33, v33, v36
	v_mul_f32_e32 v36, 0xbfb8aa3b, v40
	v_exp_f32_e32 v36, v36
	v_mul_f32_e32 v34, v40, v34
	v_pk_mul_f32 v[42:43], v[42:43], v[48:49] op_sel_hi:[1,0]
	v_mul_f32_e32 v35, v41, v35
	v_add_f32_e32 v36, 1.0, v36
	v_rcp_f32_e32 v36, v36
	v_mul_f32_e32 v37, 0xbfb8aa3b, v43
	v_exp_f32_e32 v37, v37
	v_mul_f32_e32 v34, v34, v36
	v_mul_f32_e32 v36, 0xbfb8aa3b, v41
	v_exp_f32_e32 v36, v36
	v_add_f32_e32 v37, 1.0, v37
	v_rcp_f32_e32 v37, v37
	v_add_f32_e32 v36, 1.0, v36
	v_rcp_f32_e32 v36, v36
	s_nop 0
	v_mul_f32_e32 v35, v35, v36
	v_mul_f32_e32 v36, 0xbfb8aa3b, v42
	v_exp_f32_e32 v36, v36
	v_cvt_pk_bf16_f32 v34, v34, v35
	v_mul_f32_e32 v35, v42, v50
	v_add_f32_e32 v36, 1.0, v36
	v_rcp_f32_e32 v36, v36
	s_nop 0
	v_mul_f32_e32 v35, v35, v36
	v_mul_f32_e32 v36, v43, v51
	v_mul_f32_e32 v36, v36, v37
	v_cvt_pk_bf16_f32 v35, v35, v36
	v_mad_i64_i32 v[36:37], s[10:11], v49, s24, v[112:113]
	v_lshl_add_u64 v[36:37], v[36:37], 0, v[114:115]
	global_store_dwordx4 v[36:37], v[32:35], off
	s_nop 1
	v_pk_mul_f32 v[32:33], v[18:19], v[138:139] op_sel_hi:[1,0]
	v_pk_mul_f32 v[18:19], v[16:17], v[138:139] op_sel_hi:[1,0]
	v_mul_f32_e32 v17, 0xbfb8aa3b, v28
	v_mul_f32_e32 v16, v28, v20
	v_exp_f32_e32 v17, v17
	v_mul_f32_e32 v20, 0xbfb8aa3b, v29
	v_exp_f32_e32 v20, v20
	v_mul_f32_e32 v18, v24, v18
	v_add_f32_e32 v17, 1.0, v17
	v_rcp_f32_e32 v17, v17
	v_add_f32_e32 v20, 1.0, v20
	v_rcp_f32_e32 v20, v20
	v_mul_f32_e32 v19, v25, v19
	v_mul_f32_e32 v16, v16, v17
	v_mul_f32_e32 v17, v29, v21
	v_mul_f32_e32 v17, v17, v20
	v_mul_f32_e32 v20, 0xbfb8aa3b, v30
	v_exp_f32_e32 v20, v20
	v_mul_f32_e32 v21, 0xbfb8aa3b, v31
	v_exp_f32_e32 v21, v21
	v_cvt_pk_bf16_f32 v16, v16, v17
	v_add_f32_e32 v20, 1.0, v20
	v_rcp_f32_e32 v20, v20
	v_add_f32_e32 v21, 1.0, v21
	v_rcp_f32_e32 v21, v21
	v_mul_f32_e32 v17, v30, v22
	v_mul_f32_e32 v17, v17, v20
	v_mul_f32_e32 v20, v31, v23
	v_mul_f32_e32 v20, v20, v21
	v_cvt_pk_bf16_f32 v17, v17, v20
	v_mul_f32_e32 v20, 0xbfb8aa3b, v24
	v_exp_f32_e32 v20, v20
	v_mul_f32_e32 v21, 0xbfb8aa3b, v27
	v_exp_f32_e32 v21, v21
	v_add_u32_e32 v34, 0xa0, v153
	v_add_f32_e32 v20, 1.0, v20
	v_rcp_f32_e32 v20, v20
	v_add_f32_e32 v21, 1.0, v21
	v_rcp_f32_e32 v21, v21
	v_mul_f32_e32 v18, v18, v20
	v_mul_f32_e32 v20, 0xbfb8aa3b, v25
	v_exp_f32_e32 v20, v20
	s_nop 0
	v_add_f32_e32 v20, 1.0, v20
	v_rcp_f32_e32 v20, v20
	s_nop 0
	v_mul_f32_e32 v19, v19, v20
	v_mul_f32_e32 v20, 0xbfb8aa3b, v26
	v_exp_f32_e32 v20, v20
	v_cvt_pk_bf16_f32 v18, v18, v19
	v_mul_f32_e32 v19, v26, v32
	v_add_f32_e32 v20, 1.0, v20
	v_rcp_f32_e32 v20, v20
	s_nop 0
	v_mul_f32_e32 v19, v19, v20
	v_mul_f32_e32 v20, v27, v33
	v_mul_f32_e32 v20, v20, v21
	v_cvt_pk_bf16_f32 v19, v19, v20
	v_mad_i64_i32 v[20:21], s[10:11], v34, s24, v[112:113]
	v_lshl_add_u64 v[20:21], v[20:21], 0, v[114:115]
	global_store_dwordx4 v[20:21], v[16:19], off
	s_nop 1
	v_add_u32_e32 v17, 0xb0, v153
	v_mov_b32_e32 v16, v139
	v_pk_mul_f32 v[12:13], v[12:13], v[16:17] op_sel_hi:[1,0]
	v_pk_mul_f32 v[4:5], v[4:5], v[16:17] op_sel_hi:[1,0]
	v_pk_mul_f32 v[18:19], v[2:3], v[16:17] op_sel_hi:[1,0]
	v_pk_mul_f32 v[2:3], v[0:1], v[16:17] op_sel_hi:[1,0]
; __device__ __forceinline__ unsigned cvt_pk_bf16(float lo, float hi) { unsigned r; asm volatile("v_cvt_pk_bf16_f32 %0, %1, %2" : "=v"(r) : "v"(lo), "v"(hi)); return r; }
; __device__ __forceinline__ float silu_mul(float g, float u) { return g * u * __builtin_amdgcn_rcpf(1.0f + __builtin_amdgcn_exp2f(-1.4426950408889634f * g)); }
; #define PG8_STAGE(bufoff, gbase, voff) do { _Pragma("unroll") for (int _i = 0; _i < 2; ++_i) \
;         __builtin_amdgcn_global_load_lds((const unsigned*)((const char*)(gbase) + (voff)[_i]), (PG8_LAS unsigned*)(lds + (bufoff) + ldsw + _i * 8192), 16, 0, 0); } while (0)
; #define PG8_LDA(dst, b, h) do { _Pragma("unroll") for (int m = 0; m < 4; ++m) _Pragma("unroll") for (int k = 0; k < 2; ++k) dst[m][k] = *(const PG8_LAS bf16x8*)(lds + PG8_SA(b, h) + aoff + m * 2048 + k * 1024); } while (0)
; #define PG8_LDB(dst, b, h) do { _Pragma("unroll") for (int n = 0; n < 2; ++n) _Pragma("unroll") for (int k = 0; k < 2; ++k) dst[n][k] = *(const PG8_LAS bf16x8*)(lds + PG8_SB(b, h) + boff + n * 2048 + k * 1024); } while (0)
; #define PG8_WAIT_V(n) asm volatile("s_waitcnt vmcnt(" #n ")" ::: "memory")
; #define PG8_WAIT_L(n) asm volatile("s_waitcnt lgkmcnt(" #n ")" ::: "memory")
; #define PG8_BAR __builtin_amdgcn_s_barrier()
;     __device__ __forceinline__ void operator()(const f32x4 (&acc)[2][2][4][2], const Unit& u, int wr, int wc, int fr, int fq) const {
;     ...
;                 const f32x4 g0 = acc[ai][0][m][0] * rs, g1 = acc[ai][0][m][1] * rs, u0 = acc[ai][1][m][0] * rs, u1 = acc[ai][1][m][1] * rs;
;                 u32x4e w;
;                 w.x = cvt_pk_bf16(silu_mul(g0[0], u0[0]), silu_mul(g0[1], u0[1])); w.y = cvt_pk_bf16(silu_mul(g0[2], u0[2]), silu_mul(g0[3], u0[3]));
;                 w.z = cvt_pk_bf16(silu_mul(g1[0], u1[0]), silu_mul(g1[1], u1[1])); w.w = cvt_pk_bf16(silu_mul(g1[2], u1[2]), silu_mul(g1[3], u1[3]));
;                 *(u32x4e*)(O + (size_t)row * ldo + col0) = w;
;             }
; template <class Epi, class Sched, bool ALIGN_EPI = false, bool SP2 = false>
; __device__ __forceinline__ void gemm_phase(PG8_LAS unsigned char* lds, const Gemm g, const Sched& S, const Epi& E) {
;     ...
;             PG8_LDB(B0, 0, 0); PG8_LDB(B1, 0, 1); PG8_SCHED; PG8_LDA(At, 0, 0); PG8_STAGE(PG8_SA(1, 1), a1 + hstep, voffA);
;             PG8_WAIT_V(8); PG8_WAIT_L(0); PG8_BAR; PG8_MMA(0, 0, At, B0); PG8_MMA(0, 1, At, B1); PG8_BAR; PG8_SCHED;
	v_mul_f32_e32 v1, 0xbfb8aa3b, v12
	v_mul_f32_e32 v0, v12, v4
	v_exp_f32_e32 v1, v1
	v_mul_f32_e32 v4, 0xbfb8aa3b, v13
	v_exp_f32_e32 v4, v4
	v_pk_mul_f32 v[14:15], v[14:15], v[16:17] op_sel_hi:[1,0]
	v_add_f32_e32 v1, 1.0, v1
	v_rcp_f32_e32 v1, v1
	v_add_f32_e32 v4, 1.0, v4
	v_rcp_f32_e32 v4, v4
	v_pk_mul_f32 v[6:7], v[6:7], v[16:17] op_sel_hi:[1,0]
	v_mul_f32_e32 v0, v0, v1
	v_mul_f32_e32 v1, v13, v5
	v_mul_f32_e32 v1, v1, v4
	v_mul_f32_e32 v4, 0xbfb8aa3b, v14
	v_exp_f32_e32 v4, v4
	v_mul_f32_e32 v5, 0xbfb8aa3b, v15
	v_exp_f32_e32 v5, v5
	v_cvt_pk_bf16_f32 v0, v0, v1
	v_add_f32_e32 v4, 1.0, v4
	v_rcp_f32_e32 v4, v4
	v_add_f32_e32 v5, 1.0, v5
	v_rcp_f32_e32 v5, v5
	v_mul_f32_e32 v1, v14, v6
	v_mul_f32_e32 v1, v1, v4
	v_mul_f32_e32 v4, v15, v7
	v_pk_mul_f32 v[8:9], v[8:9], v[16:17] op_sel_hi:[1,0]
	v_mul_f32_e32 v4, v4, v5
	v_cvt_pk_bf16_f32 v1, v1, v4
	v_mul_f32_e32 v4, 0xbfb8aa3b, v8
	v_exp_f32_e32 v4, v4
	v_mul_f32_e32 v2, v8, v2
	v_pk_mul_f32 v[10:11], v[10:11], v[16:17] op_sel_hi:[1,0]
	v_mul_f32_e32 v3, v9, v3
	v_add_f32_e32 v4, 1.0, v4
	v_rcp_f32_e32 v4, v4
	v_mul_f32_e32 v5, 0xbfb8aa3b, v11
	v_exp_f32_e32 v5, v5
	v_mul_f32_e32 v2, v2, v4
	v_mul_f32_e32 v4, 0xbfb8aa3b, v9
	v_exp_f32_e32 v4, v4
	v_add_f32_e32 v5, 1.0, v5
	v_rcp_f32_e32 v5, v5
	v_add_f32_e32 v4, 1.0, v4
	v_rcp_f32_e32 v4, v4
	s_nop 0
	v_mul_f32_e32 v3, v3, v4
	v_mul_f32_e32 v4, 0xbfb8aa3b, v10
	v_exp_f32_e32 v4, v4
	v_cvt_pk_bf16_f32 v2, v2, v3
	v_mul_f32_e32 v3, v10, v18
	v_add_f32_e32 v4, 1.0, v4
	v_rcp_f32_e32 v4, v4
	s_nop 0
	v_mul_f32_e32 v3, v3, v4
	v_mul_f32_e32 v4, v11, v19
	v_mul_f32_e32 v4, v4, v5
	v_cvt_pk_bf16_f32 v3, v3, v4
	v_mad_i64_i32 v[4:5], s[10:11], v17, s24, v[112:113]
	v_lshl_add_u64 v[4:5], v[4:5], 0, v[114:115]
	s_mov_b64 s[10:11], -1
	global_store_dwordx4 v[4:5], v[0:3], off
	s_cbranch_vccnz .LBB0_395
	s_andn2_b64 vcc, exec, s[4:5]
	s_cbranch_vccnz .LBB0_394
	s_barrier
	s_branch .LBB0_394
.Lpeel_act:
	s_add_u32 s12, s10, 0xfffc0080
	s_addc_u32 s13, s11, -1
	s_add_i32 s51, 0, 0x10000
	s_cmp_eq_u32 s50, 12
	s_cselect_b32 s15, s41, s13
	s_cselect_b32 s14, s46, s12
	v_add_u32_e32 v146, s51, v149
	s_cselect_b32 s13, s9, s49
	s_cselect_b32 s12, s47, s48
	s_add_i32 s54, 0, 0x14000
	ds_read_b128 v[138:141], v146
	ds_read_b128 v[142:145], v146 offset:1024
	ds_read_b128 v[168:171], v146 offset:2048
	ds_read_b128 v[172:175], v146 offset:3072
	v_add_u32_e32 v146, s54, v149
	ds_read_b128 v[176:179], v146
	ds_read_b128 v[180:183], v146 offset:1024
	ds_read_b128 v[184:187], v146 offset:2048
	ds_read_b128 v[188:191], v146 offset:3072
	ds_read_b128 v[192:195], v152
	ds_read_b128 v[196:199], v152 offset:1024
	ds_read_b128 v[200:203], v152 offset:2048
	ds_read_b128 v[204:207], v152 offset:3072
	ds_read_b128 v[208:211], v152 offset:4096
	ds_read_b128 v[212:215], v152 offset:5120
	ds_read_b128 v[216:219], v152 offset:6144
	ds_read_b128 v[220:223], v152 offset:7168
	s_waitcnt vmcnt(16)
	s_waitcnt lgkmcnt(0)
	s_barrier
	s_setprio 1
	s_waitcnt lgkmcnt(0)
	v_mfma_f32_16x16x32_bf16 v[124:127], v[138:141], v[192:195], v[124:127]
	v_mfma_f32_16x16x32_bf16 v[120:123], v[168:171], v[192:195], v[120:123]
	v_mfma_f32_16x16x32_bf16 v[108:111], v[138:141], v[200:203], v[108:111]
	v_mfma_f32_16x16x32_bf16 v[104:107], v[168:171], v[200:203], v[104:107]
	v_mfma_f32_16x16x32_bf16 v[92:95], v[138:141], v[208:211], v[92:95]
	v_mfma_f32_16x16x32_bf16 v[88:91], v[168:171], v[208:211], v[88:91]
	v_mfma_f32_16x16x32_bf16 v[76:79], v[138:141], v[216:219], v[76:79]
	v_mfma_f32_16x16x32_bf16 v[72:75], v[168:171], v[216:219], v[72:75]
	v_mfma_f32_16x16x32_bf16 v[124:127], v[142:145], v[196:199], v[124:127]
	v_mfma_f32_16x16x32_bf16 v[120:123], v[172:175], v[196:199], v[120:123]
	v_mfma_f32_16x16x32_bf16 v[108:111], v[142:145], v[204:207], v[108:111]
	v_mfma_f32_16x16x32_bf16 v[104:107], v[172:175], v[204:207], v[104:107]
	v_mfma_f32_16x16x32_bf16 v[92:95], v[142:145], v[212:215], v[92:95]
	v_mfma_f32_16x16x32_bf16 v[88:91], v[172:175], v[212:215], v[88:91]
	v_mfma_f32_16x16x32_bf16 v[76:79], v[142:145], v[220:223], v[76:79]
	v_mfma_f32_16x16x32_bf16 v[72:75], v[172:175], v[220:223], v[72:75]
	s_setprio 0
	s_setprio 1
	v_mfma_f32_16x16x32_bf16 v[116:119], v[176:179], v[192:195], v[116:119]
	v_mfma_f32_16x16x32_bf16 v[112:115], v[184:187], v[192:195], v[112:115]
	v_mfma_f32_16x16x32_bf16 v[100:103], v[176:179], v[200:203], v[100:103]
	v_mfma_f32_16x16x32_bf16 v[96:99], v[184:187], v[200:203], v[96:99]
	v_mfma_f32_16x16x32_bf16 v[84:87], v[176:179], v[208:211], v[84:87]
	v_mfma_f32_16x16x32_bf16 v[80:83], v[184:187], v[208:211], v[80:83]
	v_mfma_f32_16x16x32_bf16 v[68:71], v[176:179], v[216:219], v[68:71]
	v_mfma_f32_16x16x32_bf16 v[64:67], v[184:187], v[216:219], v[64:67]
	v_mfma_f32_16x16x32_bf16 v[116:119], v[180:183], v[196:199], v[116:119]
	v_mfma_f32_16x16x32_bf16 v[112:115], v[188:191], v[196:199], v[112:115]
	v_mfma_f32_16x16x32_bf16 v[100:103], v[180:183], v[204:207], v[100:103]
	v_mfma_f32_16x16x32_bf16 v[96:99], v[188:191], v[204:207], v[96:99]
	v_mfma_f32_16x16x32_bf16 v[84:87], v[180:183], v[212:215], v[84:87]
	v_mfma_f32_16x16x32_bf16 v[80:83], v[188:191], v[212:215], v[80:83]
	v_mfma_f32_16x16x32_bf16 v[68:71], v[180:183], v[220:223], v[68:71]
	v_mfma_f32_16x16x32_bf16 v[64:67], v[188:191], v[220:223], v[64:67]
	s_setprio 0
	s_barrier
; #define PG8_STAGE(bufoff, gbase, voff) do { _Pragma("unroll") for (int _i = 0; _i < 2; ++_i) \
;         __builtin_amdgcn_global_load_lds((const unsigned*)((const char*)(gbase) + (voff)[_i]), (PG8_LAS unsigned*)(lds + (bufoff) + ldsw + _i * 8192), 16, 0, 0); } while (0)
; #define PG8_LDA(dst, b, h) do { _Pragma("unroll") for (int m = 0; m < 4; ++m) _Pragma("unroll") for (int k = 0; k < 2; ++k) dst[m][k] = *(const PG8_LAS bf16x8*)(lds + PG8_SA(b, h) + aoff + m * 2048 + k * 1024); } while (0)
; #define PG8_LDB(dst, b, h) do { _Pragma("unroll") for (int n = 0; n < 2; ++n) _Pragma("unroll") for (int k = 0; k < 2; ++k) dst[n][k] = *(const PG8_LAS bf16x8*)(lds + PG8_SB(b, h) + boff + n * 2048 + k * 1024); } while (0)
; #define PG8_MMA(ai, bj, At, Bt) do { __builtin_amdgcn_s_setprio(1); _Pragma("unroll") for (int m = 0; m < 4; ++m) _Pragma("unroll") for (int n = 0; n < 2; ++n) _Pragma("unroll") for (int k = 0; k < 2; ++k) \
;         acc[ai][bj][m][n] = __builtin_amdgcn_mfma_f32_16x16x32_bf16(Bt[n][k], At[m][k], acc[ai][bj][m][n], 0, 0, 0); __builtin_amdgcn_s_setprio(0); } while (0)
; #define PG8_WAIT_V(n) asm volatile("s_waitcnt vmcnt(" #n ")" ::: "memory")
; #define PG8_WAIT_L(n) asm volatile("s_waitcnt lgkmcnt(" #n ")" ::: "memory")
; #define PG8_BAR __builtin_amdgcn_s_barrier()
; #define PG8_SCHED __builtin_amdgcn_sched_barrier(0)
; template <class Epi, class Sched, bool ALIGN_EPI = false, bool SP2 = false>
; __device__ __forceinline__ void gemm_phase(PG8_LAS unsigned char* lds, const Gemm g, const Sched& S, const Epi& E) {
;     ...
;             PG8_WAIT_V(8); PG8_WAIT_L(0); PG8_BAR; PG8_MMA(0, 0, At, B0); PG8_MMA(0, 1, At, B1); PG8_BAR; PG8_SCHED;
;             PG8_LDA(At, 0, 1); PG8_STAGE(PG8_SB(0, 0), b2, voffB); PG8_STAGE(PG8_SB(0, 1), b2 + hstep, voffB); PG8_STAGE(PG8_SA(0, 0), a2, voffA);
;             PG8_WAIT_V(8); PG8_WAIT_L(0); PG8_BAR; PG8_MMA(1, 0, At, B0); PG8_MMA(1, 1, At, B1); PG8_BAR; PG8_SCHED;
;             PG8_LDB(B0, 1, 0); PG8_LDB(B1, 1, 1); PG8_SCHED; PG8_LDA(At, 1, 0); PG8_STAGE(PG8_SA(0, 1), a2 + hstep, voffA);
	s_add_i32 s51, s51, s21
	v_lshl_add_u64 v[146:147], s[12:13], 0, v[156:157]
	s_mov_b32 m0, s51
	ds_read_b128 v[192:195], v152 offset:16384
	ds_read_b128 v[196:199], v152 offset:17408
	ds_read_b128 v[200:203], v152 offset:18432
	ds_read_b128 v[204:207], v152 offset:19456
	ds_read_b128 v[208:211], v152 offset:20480
	ds_read_b128 v[212:215], v152 offset:21504
	ds_read_b128 v[216:219], v152 offset:22528
	ds_read_b128 v[220:223], v152 offset:23552
	global_load_lds_dwordx4 v[146:147], off
	s_add_i32 m0, s51, 0x2000
	s_add_u32 s52, s12, 0x40000
	v_lshl_add_u64 v[154:155], s[12:13], 0, v[128:129]
	s_addc_u32 s53, s13, 0
	s_add_i32 s51, s54, s21
	global_load_lds_dwordx4 v[154:155], off
	v_lshl_add_u64 v[224:225], s[52:53], 0, v[156:157]
	s_mov_b32 m0, s51
	v_lshl_add_u64 v[226:227], s[14:15], 0, v[130:131]
	global_load_lds_dwordx4 v[224:225], off
	v_lshl_add_u64 v[224:225], s[52:53], 0, v[128:129]
	s_add_i32 m0, s51, 0x2000
	s_nop 0
	global_load_lds_dwordx4 v[224:225], off
	v_lshl_add_u64 v[224:225], s[14:15], 0, v[132:133]
	s_mov_b32 m0, s25
	s_nop 0
	global_load_lds_dwordx4 v[224:225], off
	s_mov_b32 m0, s26
	s_nop 0
	global_load_lds_dwordx4 v[226:227], off
	s_waitcnt vmcnt(16)
	s_waitcnt lgkmcnt(0)
	s_barrier
	s_setprio 1
	s_waitcnt lgkmcnt(0)
	v_mfma_f32_16x16x32_bf16 v[60:63], v[138:141], v[192:195], v[60:63]
	v_mfma_f32_16x16x32_bf16 v[56:59], v[168:171], v[192:195], v[56:59]
	v_mfma_f32_16x16x32_bf16 v[44:47], v[138:141], v[200:203], v[44:47]
	v_mfma_f32_16x16x32_bf16 v[40:43], v[168:171], v[200:203], v[40:43]
	v_mfma_f32_16x16x32_bf16 v[28:31], v[138:141], v[208:211], v[28:31]
	v_mfma_f32_16x16x32_bf16 v[24:27], v[168:171], v[208:211], v[24:27]
	v_mfma_f32_16x16x32_bf16 v[12:15], v[138:141], v[216:219], v[12:15]
	v_mfma_f32_16x16x32_bf16 v[8:11], v[168:171], v[216:219], v[8:11]
	v_mfma_f32_16x16x32_bf16 v[60:63], v[142:145], v[196:199], v[60:63]
	v_mfma_f32_16x16x32_bf16 v[56:59], v[172:175], v[196:199], v[56:59]
	v_mfma_f32_16x16x32_bf16 v[44:47], v[142:145], v[204:207], v[44:47]
	v_mfma_f32_16x16x32_bf16 v[40:43], v[172:175], v[204:207], v[40:43]
	v_mfma_f32_16x16x32_bf16 v[28:31], v[142:145], v[212:215], v[28:31]
	v_mfma_f32_16x16x32_bf16 v[24:27], v[172:175], v[212:215], v[24:27]
	v_mfma_f32_16x16x32_bf16 v[12:15], v[142:145], v[220:223], v[12:15]
	v_mfma_f32_16x16x32_bf16 v[8:11], v[172:175], v[220:223], v[8:11]
	s_setprio 0
	s_setprio 1
	v_mfma_f32_16x16x32_bf16 v[52:55], v[176:179], v[192:195], v[52:55]
	v_mfma_f32_16x16x32_bf16 v[48:51], v[184:187], v[192:195], v[48:51]
	v_mfma_f32_16x16x32_bf16 v[36:39], v[176:179], v[200:203], v[36:39]
	v_mfma_f32_16x16x32_bf16 v[32:35], v[184:187], v[200:203], v[32:35]
	v_mfma_f32_16x16x32_bf16 v[20:23], v[176:179], v[208:211], v[20:23]
	v_mfma_f32_16x16x32_bf16 v[16:19], v[184:187], v[208:211], v[16:19]
	v_mfma_f32_16x16x32_bf16 v[4:7], v[176:179], v[216:219], v[4:7]
	v_mfma_f32_16x16x32_bf16 v[0:3], v[184:187], v[216:219], v[0:3]
	v_mfma_f32_16x16x32_bf16 v[52:55], v[180:183], v[196:199], v[52:55]
	v_mfma_f32_16x16x32_bf16 v[48:51], v[188:191], v[196:199], v[48:51]
	v_mfma_f32_16x16x32_bf16 v[36:39], v[180:183], v[204:207], v[36:39]
	v_mfma_f32_16x16x32_bf16 v[32:35], v[188:191], v[204:207], v[32:35]
	v_mfma_f32_16x16x32_bf16 v[20:23], v[180:183], v[212:215], v[20:23]
	v_mfma_f32_16x16x32_bf16 v[16:19], v[188:191], v[212:215], v[16:19]
	v_mfma_f32_16x16x32_bf16 v[4:7], v[180:183], v[220:223], v[4:7]
	v_mfma_f32_16x16x32_bf16 v[0:3], v[188:191], v[220:223], v[0:3]
	s_setprio 0
	s_barrier
	s_add_i32 s51, 0, 0x18000
	v_add_u32_e32 v153, s51, v149
	s_add_i32 s52, 0, 0x1c000
	ds_read_b128 v[138:141], v153
	ds_read_b128 v[142:145], v153 offset:1024
	ds_read_b128 v[168:171], v153 offset:2048
	ds_read_b128 v[172:175], v153 offset:3072
	v_add_u32_e32 v153, s52, v149
	ds_read_b128 v[176:179], v153
	ds_read_b128 v[180:183], v153 offset:1024
	ds_read_b128 v[184:187], v153 offset:2048
	ds_read_b128 v[188:191], v153 offset:3072
	s_add_u32 s14, s14, 0x40000
	s_addc_u32 s15, s15, 0
	s_mov_b32 m0, s27
	v_lshl_add_u64 v[228:229], s[14:15], 0, v[132:133]
	ds_read_b128 v[192:195], v152 offset:32768
	ds_read_b128 v[196:199], v152 offset:33792
	ds_read_b128 v[200:203], v152 offset:34816
	ds_read_b128 v[204:207], v152 offset:35840
	ds_read_b128 v[208:211], v152 offset:36864
	ds_read_b128 v[212:215], v152 offset:37888
	ds_read_b128 v[216:219], v152 offset:38912
	ds_read_b128 v[220:223], v152 offset:39936
	global_load_lds_dwordx4 v[228:229], off
	v_lshl_add_u64 v[228:229], s[14:15], 0, v[130:131]
	s_mov_b32 m0, s28
	s_nop 0
	global_load_lds_dwordx4 v[228:229], off
	s_waitcnt vmcnt(16)
	s_waitcnt lgkmcnt(0)
	s_barrier
; #define PG8_STAGE(bufoff, gbase, voff) do { _Pragma("unroll") for (int _i = 0; _i < 2; ++_i) \
;         __builtin_amdgcn_global_load_lds((const unsigned*)((const char*)(gbase) + (voff)[_i]), (PG8_LAS unsigned*)(lds + (bufoff) + ldsw + _i * 8192), 16, 0, 0); } while (0)
; #define PG8_LDA(dst, b, h) do { _Pragma("unroll") for (int m = 0; m < 4; ++m) _Pragma("unroll") for (int k = 0; k < 2; ++k) dst[m][k] = *(const PG8_LAS bf16x8*)(lds + PG8_SA(b, h) + aoff + m * 2048 + k * 1024); } while (0)
; #define PG8_LDB(dst, b, h) do { _Pragma("unroll") for (int n = 0; n < 2; ++n) _Pragma("unroll") for (int k = 0; k < 2; ++k) dst[n][k] = *(const PG8_LAS bf16x8*)(lds + PG8_SB(b, h) + boff + n * 2048 + k * 1024); } while (0)
; #define PG8_MMA(ai, bj, At, Bt) do { __builtin_amdgcn_s_setprio(1); _Pragma("unroll") for (int m = 0; m < 4; ++m) _Pragma("unroll") for (int n = 0; n < 2; ++n) _Pragma("unroll") for (int k = 0; k < 2; ++k) \
;         acc[ai][bj][m][n] = __builtin_amdgcn_mfma_f32_16x16x32_bf16(Bt[n][k], At[m][k], acc[ai][bj][m][n], 0, 0, 0); __builtin_amdgcn_s_setprio(0); } while (0)
; #define PG8_WAIT_V(n) asm volatile("s_waitcnt vmcnt(" #n ")" ::: "memory")
; #define PG8_WAIT_L(n) asm volatile("s_waitcnt lgkmcnt(" #n ")" ::: "memory")
; #define PG8_BAR __builtin_amdgcn_s_barrier()
; #define PG8_SCHED __builtin_amdgcn_sched_barrier(0)
; template <class Epi, class Sched, bool ALIGN_EPI = false, bool SP2 = false>
; __device__ __forceinline__ void gemm_phase(PG8_LAS unsigned char* lds, const Gemm g, const Sched& S, const Epi& E) {
;     ...
;             PG8_LDB(B0, 1, 0); PG8_LDB(B1, 1, 1); PG8_SCHED; PG8_LDA(At, 1, 0); PG8_STAGE(PG8_SA(0, 1), a2 + hstep, voffA);
;             PG8_WAIT_V(8); PG8_WAIT_L(0); PG8_BAR; PG8_MMA(0, 0, At, B0); PG8_MMA(0, 1, At, B1); PG8_BAR; PG8_SCHED;
;             PG8_LDA(At, 1, 1); PG8_STAGE(PG8_SB(1, 0), b3, voffB); PG8_STAGE(PG8_SB(1, 1), b3 + hstep, voffB); PG8_STAGE(PG8_SA(1, 0), a3, voffA);
;             PG8_WAIT_V(8); PG8_WAIT_L(0); PG8_BAR; PG8_MMA(1, 0, At, B0); PG8_MMA(1, 1, At, B1); PG8_BAR; PG8_SCHED;
	s_setprio 1
	s_waitcnt lgkmcnt(0)
	v_mfma_f32_16x16x32_bf16 v[124:127], v[138:141], v[192:195], v[124:127]
	v_mfma_f32_16x16x32_bf16 v[120:123], v[168:171], v[192:195], v[120:123]
	v_mfma_f32_16x16x32_bf16 v[108:111], v[138:141], v[200:203], v[108:111]
	v_mfma_f32_16x16x32_bf16 v[104:107], v[168:171], v[200:203], v[104:107]
	v_mfma_f32_16x16x32_bf16 v[92:95], v[138:141], v[208:211], v[92:95]
	v_mfma_f32_16x16x32_bf16 v[88:91], v[168:171], v[208:211], v[88:91]
	v_mfma_f32_16x16x32_bf16 v[76:79], v[138:141], v[216:219], v[76:79]
	v_mfma_f32_16x16x32_bf16 v[72:75], v[168:171], v[216:219], v[72:75]
	v_mfma_f32_16x16x32_bf16 v[124:127], v[142:145], v[196:199], v[124:127]
	v_mfma_f32_16x16x32_bf16 v[120:123], v[172:175], v[196:199], v[120:123]
	v_mfma_f32_16x16x32_bf16 v[108:111], v[142:145], v[204:207], v[108:111]
	v_mfma_f32_16x16x32_bf16 v[104:107], v[172:175], v[204:207], v[104:107]
	v_mfma_f32_16x16x32_bf16 v[92:95], v[142:145], v[212:215], v[92:95]
	v_mfma_f32_16x16x32_bf16 v[88:91], v[172:175], v[212:215], v[88:91]
	v_mfma_f32_16x16x32_bf16 v[76:79], v[142:145], v[220:223], v[76:79]
	v_mfma_f32_16x16x32_bf16 v[72:75], v[172:175], v[220:223], v[72:75]
	s_setprio 0
	s_setprio 1
	v_mfma_f32_16x16x32_bf16 v[116:119], v[176:179], v[192:195], v[116:119]
	v_mfma_f32_16x16x32_bf16 v[112:115], v[184:187], v[192:195], v[112:115]
	v_mfma_f32_16x16x32_bf16 v[100:103], v[176:179], v[200:203], v[100:103]
	v_mfma_f32_16x16x32_bf16 v[96:99], v[184:187], v[200:203], v[96:99]
	v_mfma_f32_16x16x32_bf16 v[84:87], v[176:179], v[208:211], v[84:87]
	v_mfma_f32_16x16x32_bf16 v[80:83], v[184:187], v[208:211], v[80:83]
	v_mfma_f32_16x16x32_bf16 v[68:71], v[176:179], v[216:219], v[68:71]
	v_mfma_f32_16x16x32_bf16 v[64:67], v[184:187], v[216:219], v[64:67]
	v_mfma_f32_16x16x32_bf16 v[116:119], v[180:183], v[196:199], v[116:119]
	v_mfma_f32_16x16x32_bf16 v[112:115], v[188:191], v[196:199], v[112:115]
	v_mfma_f32_16x16x32_bf16 v[100:103], v[180:183], v[204:207], v[100:103]
	v_mfma_f32_16x16x32_bf16 v[96:99], v[188:191], v[204:207], v[96:99]
	v_mfma_f32_16x16x32_bf16 v[84:87], v[180:183], v[212:215], v[84:87]
	v_mfma_f32_16x16x32_bf16 v[80:83], v[188:191], v[212:215], v[80:83]
	v_mfma_f32_16x16x32_bf16 v[68:71], v[180:183], v[220:223], v[68:71]
	v_mfma_f32_16x16x32_bf16 v[64:67], v[188:191], v[220:223], v[64:67]
	s_setprio 0
	s_barrier
	s_add_i32 s14, s51, s21
	v_lshl_add_u64 v[146:147], v[146:147], 0, s[96:97]
	s_mov_b32 m0, s14
	ds_read_b128 v[192:195], v152 offset:49152
	ds_read_b128 v[196:199], v152 offset:50176
	ds_read_b128 v[200:203], v152 offset:51200
	ds_read_b128 v[204:207], v152 offset:52224
	ds_read_b128 v[208:211], v152 offset:53248
	ds_read_b128 v[212:215], v152 offset:54272
	ds_read_b128 v[216:219], v152 offset:55296
	ds_read_b128 v[220:223], v152 offset:56320
	global_load_lds_dwordx4 v[146:147], off
	s_add_i32 m0, s14, 0x2000
	s_add_u32 s12, s12, 0x40080
	v_lshl_add_u64 v[146:147], v[154:155], 0, s[96:97]
	s_addc_u32 s13, s13, 0
	s_add_i32 s14, s52, s21
	global_load_lds_dwordx4 v[146:147], off
	v_lshl_add_u64 v[146:147], s[12:13], 0, v[156:157]
	s_mov_b32 m0, s14
	s_nop 0
	global_load_lds_dwordx4 v[146:147], off
	v_lshl_add_u64 v[146:147], s[12:13], 0, v[128:129]
	s_add_i32 m0, s14, 0x2000
	s_nop 0
	global_load_lds_dwordx4 v[146:147], off
	v_lshl_add_u64 v[146:147], v[224:225], 0, s[96:97]
	s_mov_b32 m0, s29
	s_nop 0
	global_load_lds_dwordx4 v[146:147], off
	v_lshl_add_u64 v[146:147], v[226:227], 0, s[96:97]
	s_mov_b32 m0, s30
	s_nop 0
	global_load_lds_dwordx4 v[146:147], off
	s_waitcnt vmcnt(8)
	s_waitcnt lgkmcnt(0)
	s_barrier
	s_setprio 1
	s_waitcnt lgkmcnt(0)
	v_mfma_f32_16x16x32_bf16 v[60:63], v[138:141], v[192:195], v[60:63]
	v_mfma_f32_16x16x32_bf16 v[56:59], v[168:171], v[192:195], v[56:59]
	v_mfma_f32_16x16x32_bf16 v[44:47], v[138:141], v[200:203], v[44:47]
	v_mfma_f32_16x16x32_bf16 v[40:43], v[168:171], v[200:203], v[40:43]
	v_mfma_f32_16x16x32_bf16 v[28:31], v[138:141], v[208:211], v[28:31]
	v_mfma_f32_16x16x32_bf16 v[24:27], v[168:171], v[208:211], v[24:27]
	v_mfma_f32_16x16x32_bf16 v[12:15], v[138:141], v[216:219], v[12:15]
	v_mfma_f32_16x16x32_bf16 v[8:11], v[168:171], v[216:219], v[8:11]
	v_mfma_f32_16x16x32_bf16 v[60:63], v[142:145], v[196:199], v[60:63]
	v_mfma_f32_16x16x32_bf16 v[56:59], v[172:175], v[196:199], v[56:59]
	v_mfma_f32_16x16x32_bf16 v[44:47], v[142:145], v[204:207], v[44:47]
	v_mfma_f32_16x16x32_bf16 v[40:43], v[172:175], v[204:207], v[40:43]
	v_mfma_f32_16x16x32_bf16 v[28:31], v[142:145], v[212:215], v[28:31]
	v_mfma_f32_16x16x32_bf16 v[24:27], v[172:175], v[212:215], v[24:27]
	v_mfma_f32_16x16x32_bf16 v[12:15], v[142:145], v[220:223], v[12:15]
	v_mfma_f32_16x16x32_bf16 v[8:11], v[172:175], v[220:223], v[8:11]
	s_setprio 0
	s_setprio 1
	v_mfma_f32_16x16x32_bf16 v[52:55], v[176:179], v[192:195], v[52:55]
	v_mfma_f32_16x16x32_bf16 v[48:51], v[184:187], v[192:195], v[48:51]
	v_mfma_f32_16x16x32_bf16 v[36:39], v[176:179], v[200:203], v[36:39]
	v_mfma_f32_16x16x32_bf16 v[32:35], v[184:187], v[200:203], v[32:35]
	v_mfma_f32_16x16x32_bf16 v[20:23], v[176:179], v[208:211], v[20:23]
	v_mfma_f32_16x16x32_bf16 v[16:19], v[184:187], v[208:211], v[16:19]
	v_mfma_f32_16x16x32_bf16 v[4:7], v[176:179], v[216:219], v[4:7]
	v_mfma_f32_16x16x32_bf16 v[0:3], v[184:187], v[216:219], v[0:3]
	v_mfma_f32_16x16x32_bf16 v[52:55], v[180:183], v[196:199], v[52:55]
	v_mfma_f32_16x16x32_bf16 v[48:51], v[188:191], v[196:199], v[48:51]
	v_mfma_f32_16x16x32_bf16 v[36:39], v[180:183], v[204:207], v[36:39]
	v_mfma_f32_16x16x32_bf16 v[32:35], v[188:191], v[204:207], v[32:35]
	v_mfma_f32_16x16x32_bf16 v[20:23], v[180:183], v[212:215], v[20:23]
	v_mfma_f32_16x16x32_bf16 v[16:19], v[188:191], v[212:215], v[16:19]
	v_mfma_f32_16x16x32_bf16 v[4:7], v[180:183], v[220:223], v[4:7]
	v_mfma_f32_16x16x32_bf16 v[0:3], v[188:191], v[220:223], v[0:3]
	s_setprio 0
	s_barrier
	s_add_i32 s50, s50, 2
	s_add_u32 s10, s10, 0x100
	s_addc_u32 s11, s11, 0
	s_add_u32 s48, s48, 0x100
	s_addc_u32 s49, s49, 0
	s_branch .LBB0_399
